# hot QK block: K fragment LDS reads software-pipelined one pair ahead (plain 32-bit init), on top of head-split
# baseline (speedup 1.0000x reference)
.LBB0_883:
	s_andn2_b64 vcc, exec, s[28:29]
	s_cbranch_vccnz .LBB0_885
	v_mad_u32_u24 v203, v203, s82, v201
	ds_read_b128 v[204:207], v203
	ds_read_b128 v[208:211], v203 offset:32
	ds_read_b128 v[246:249], v203 offset:64
	ds_read_b128 v[250:253], v203 offset:96
	s_nop 5
	v_xor_b32_e32 v80, 0x80000000, v199
	v_mov_b32_e32 v81, v80
	v_mov_b32_e32 v82, v80
	v_mov_b32_e32 v83, v80
	v_mov_b32_e32 v84, v80
	v_mov_b32_e32 v85, v80
	v_mov_b32_e32 v86, v80
	v_mov_b32_e32 v87, v80
	v_mov_b32_e32 v88, v80
	v_mov_b32_e32 v89, v80
	v_mov_b32_e32 v90, v80
	v_mov_b32_e32 v91, v80
	v_mov_b32_e32 v92, v80
	v_mov_b32_e32 v93, v80
	v_mov_b32_e32 v94, v80
	v_mov_b32_e32 v95, v80
	s_waitcnt lgkmcnt(2)
	v_mfma_f32_32x32x16_bf16 v[80:95], v[204:207], v[96:99], v[80:95]
	v_xor_b32_e32 v64, 0x80000000, v200
	v_mov_b32_e32 v65, v64
	v_mov_b32_e32 v66, v64
	v_mov_b32_e32 v67, v64
	v_mov_b32_e32 v68, v64
	v_mov_b32_e32 v69, v64
	v_mov_b32_e32 v70, v64
	v_mov_b32_e32 v71, v64
	v_mov_b32_e32 v72, v64
	v_mov_b32_e32 v73, v64
	v_mov_b32_e32 v74, v64
	v_mov_b32_e32 v75, v64
	v_mov_b32_e32 v76, v64
	v_mov_b32_e32 v77, v64
	v_mov_b32_e32 v78, v64
	v_mov_b32_e32 v79, v64
	v_mfma_f32_32x32x16_bf16 v[64:79], v[204:207], v[136:139], v[64:79]
	v_mfma_f32_32x32x16_bf16 v[80:95], v[208:211], v[100:103], v[80:95]
	v_mfma_f32_32x32x16_bf16 v[64:79], v[208:211], v[120:123], v[64:79]
	ds_read_b128 v[204:207], v203 offset:128
	ds_read_b128 v[208:211], v203 offset:160
	s_waitcnt lgkmcnt(2)
	v_mfma_f32_32x32x16_bf16 v[80:95], v[246:249], v[104:107], v[80:95]
	v_mfma_f32_32x32x16_bf16 v[64:79], v[246:249], v[124:127], v[64:79]
	v_mfma_f32_32x32x16_bf16 v[80:95], v[250:253], v[108:111], v[80:95]
	v_mfma_f32_32x32x16_bf16 v[64:79], v[250:253], v[128:131], v[64:79]
	s_waitcnt lgkmcnt(0)
	v_mfma_f32_32x32x16_bf16 v[80:95], v[204:207], v[112:115], v[80:95]
	v_mfma_f32_32x32x16_bf16 v[64:79], v[204:207], v[132:135], v[64:79]
	v_mfma_f32_32x32x16_bf16 v[80:95], v[208:211], v[116:119], v[80:95]
	v_mfma_f32_32x32x16_bf16 v[64:79], v[208:211], v[140:143], v[64:79]
	s_branch .LBB0_885

.LBB0_2117:
	s_andn2_b64 vcc, exec, s[34:35]
	s_cbranch_vccnz .LBB0_2119
	v_mad_u32_u24 v203, v203, s81, v201
	ds_read_b128 v[204:207], v203
	ds_read_b128 v[208:211], v203 offset:32
	ds_read_b128 v[246:249], v203 offset:64
	ds_read_b128 v[250:253], v203 offset:96
	s_nop 5
	v_xor_b32_e32 v80, 0x80000000, v199
	v_mov_b32_e32 v81, v80
	v_mov_b32_e32 v82, v80
	v_mov_b32_e32 v83, v80
	v_mov_b32_e32 v84, v80
	v_mov_b32_e32 v85, v80
	v_mov_b32_e32 v86, v80
	v_mov_b32_e32 v87, v80
	v_mov_b32_e32 v88, v80
	v_mov_b32_e32 v89, v80
	v_mov_b32_e32 v90, v80
	v_mov_b32_e32 v91, v80
	v_mov_b32_e32 v92, v80
	v_mov_b32_e32 v93, v80
	v_mov_b32_e32 v94, v80
	v_mov_b32_e32 v95, v80
	s_waitcnt lgkmcnt(2)
	v_mfma_f32_32x32x16_bf16 v[80:95], v[204:207], v[96:99], v[80:95]
	v_xor_b32_e32 v64, 0x80000000, v200
	v_mov_b32_e32 v65, v64
	v_mov_b32_e32 v66, v64
	v_mov_b32_e32 v67, v64
	v_mov_b32_e32 v68, v64
	v_mov_b32_e32 v69, v64
	v_mov_b32_e32 v70, v64
	v_mov_b32_e32 v71, v64
	v_mov_b32_e32 v72, v64
	v_mov_b32_e32 v73, v64
	v_mov_b32_e32 v74, v64
	v_mov_b32_e32 v75, v64
	v_mov_b32_e32 v76, v64
	v_mov_b32_e32 v77, v64
	v_mov_b32_e32 v78, v64
	v_mov_b32_e32 v79, v64
	v_mfma_f32_32x32x16_bf16 v[64:79], v[204:207], v[136:139], v[64:79]
	v_mfma_f32_32x32x16_bf16 v[80:95], v[208:211], v[100:103], v[80:95]
	v_mfma_f32_32x32x16_bf16 v[64:79], v[208:211], v[120:123], v[64:79]
	ds_read_b128 v[204:207], v203 offset:128
	ds_read_b128 v[208:211], v203 offset:160
	s_waitcnt lgkmcnt(2)
	v_mfma_f32_32x32x16_bf16 v[80:95], v[246:249], v[104:107], v[80:95]
	v_mfma_f32_32x32x16_bf16 v[64:79], v[246:249], v[124:127], v[64:79]
	v_mfma_f32_32x32x16_bf16 v[80:95], v[250:253], v[108:111], v[80:95]
	v_mfma_f32_32x32x16_bf16 v[64:79], v[250:253], v[128:131], v[64:79]
	s_waitcnt lgkmcnt(0)
	v_mfma_f32_32x32x16_bf16 v[80:95], v[204:207], v[112:115], v[80:95]
	v_mfma_f32_32x32x16_bf16 v[64:79], v[204:207], v[132:135], v[64:79]
	v_mfma_f32_32x32x16_bf16 v[80:95], v[208:211], v[116:119], v[80:95]
	v_mfma_f32_32x32x16_bf16 v[64:79], v[208:211], v[140:143], v[64:79]
	s_branch .LBB0_2119
